# nt attention-load version plus nt on the mLSTM state-pass row loads
# speedup vs baseline: 1.0093x; 1.0027x over previous
; #define LAS __attribute__((address_space(3)))
; DI unsigned pk2(float lo, float hi) { f32x2n v = {lo, hi}; bf16x2n b = __builtin_convertvector(v, bf16x2n); return __builtin_bit_cast(unsigned, b); }
; template <bool P2>
; DI void ml_pass(LAS unsigned char* lds, const bf16_t* PROJ, const float* GATES, float* STATE, float* SC, bf16_t* YM,
;                 const float* convw, const float* convb, const float* ogain, int G, int bid) {
;     ...
;             const float wk = __expf(b_last + gq - m_new);
;             const float mt = fmaxf(bcum + m_prev, bcum + pm);
;             const float inter = __expf(bcum + m_prev - mt);
;             if (w == 0) gs[lane] = gq;
;             const int sp = tid & 31, pc = tid >> 5;
;             {
;                 u32x4 xr[5];
;                 const bf16_t* kb = PROJ + (row0 + 2 * sp) * 3072 + 512 + 128 * h + 8 * pc;
; #pragma unroll
;                 for (int r = 0; r < 5; ++r) { const int tt = t0 + 2 * sp - 3 + r; xr[r] = (tt >= 0) ? *(const u32x4*)(kb + ((long)r - 3) * 3072) : (u32x4){0u, 0u, 0u, 0u}; }
;                 float y0[8], y1[8]; conv2(xr, cw + 640, 8 * pc, y0, y1);
;                 if (P2) { u32x4 o; o.x = pk2(y0[0], y0[1]); o.y = pk2(y0[2], y0[3]); o.z = pk2(y0[4], y0[5]); o.w = pk2(y0[6], y0[7]); *(LAS u32x4*)(Ks + (2 * sp) * 136 + 8 * pc) = o;
;                     o.x = pk2(y1[0], y1[1]); o.y = pk2(y1[2], y1[3]); o.z = pk2(y1[4], y1[5]); o.w = pk2(y1[6], y1[7]); *(LAS u32x4*)(Ks + (2 * sp + 1) * 136 + 8 * pc) = o; }
;                 const float wk0 = __shfl(wk, 2 * sp), wk1 = __shfl(wk, 2 * sp + 1);
; #pragma unroll
;                 for (int j = 0; j < 8; ++j) Kt32[(8 * pc + j) * 36 + sp] = pk2(y0[j] * wk0, y1[j] * wk1);
.LBB0_198:
	v_and_b32_e32 v147, 31, v146
	v_lshlrev_b32_e32 v112, 1, v147
	v_or_b32_e32 v66, s2, v112
	v_mov_b64_e32 v[64:65], s[28:29]
	v_mad_u64_u32 v[136:137], s[58:59], v66, s79, v[64:65]
	v_ashrrev_i32_e32 v149, 2, v146
	v_mad_i32_i24 v137, s1, v231, v137
	v_and_b32_e32 v140, -8, v149
	v_lshl_add_u64 v[64:65], v[136:137], 0, s[34:35]
	v_ashrrev_i32_e32 v141, 31, v140
	v_or_b32_e32 v69, s0, v112
	v_lshl_add_u64 v[80:81], v[140:141], 1, v[64:65]
	v_cmp_lt_u32_e32 vcc, 2, v69
	v_mov_b32_e32 v68, 0
	v_mov_b32_e32 v64, 0
	v_mov_b32_e32 v65, 0
	v_mov_b32_e32 v66, 0
	v_mov_b32_e32 v67, 0
	s_and_saveexec_b64 s[0:1], vcc
	s_cbranch_execz .LBB0_200
	v_add_co_u32_e32 v64, vcc, 0xffffc000, v80
	s_nop 1
	v_addc_co_u32_e32 v65, vcc, -1, v81, vcc
	global_load_dwordx4 v[64:67], v[64:65], off offset:-1024 nt
.LBB0_200:
	s_or_b64 exec, exec, s[0:1]
	v_cmp_ne_u32_e64 s[0:1], 0, v69
	v_mov_b32_e32 v69, 0
	v_mov_b32_e32 v70, 0
	v_mov_b32_e32 v71, 0
	s_and_saveexec_b64 s[58:59], s[0:1]
	s_cbranch_execz .LBB0_202
	v_add_co_u32_e32 v68, vcc, 0xffffe000, v80
	s_nop 1
	v_addc_co_u32_e32 v69, vcc, -1, v81, vcc
	global_load_dwordx4 v[68:71], v[68:69], off offset:-3072 nt
.LBB0_202:
	s_or_b64 exec, exec, s[58:59]
	v_mov_b32_e32 v72, 0
	v_mov_b32_e32 v73, 0
	v_mov_b32_e32 v74, 0
	v_mov_b32_e32 v75, 0
	s_and_saveexec_b64 s[58:59], s[0:1]
	s_cbranch_execz .LBB0_204
	v_add_co_u32_e32 v72, vcc, 0xfffff000, v80
	s_nop 1
	v_addc_co_u32_e32 v73, vcc, -1, v81, vcc
	global_load_dwordx4 v[72:75], v[72:73], off offset:-1024 nt
.LBB0_204:
	s_or_b64 exec, exec, s[58:59]
	v_mov_b32_e32 v77, s57
	v_add_f32_e32 v148, s71, v134
	v_add_f32_e32 v77, s71, v77
	v_max_f32_e32 v134, v148, v77
	v_add_f32_e32 v76, s71, v76
	v_sub_f32_e32 v76, v76, v134
	v_mul_f32_e32 v76, 0x3fb8aa3b, v76
	v_exp_f32_e32 v139, v76
	global_load_dwordx4 v[76:79], v[80:81], off offset:1024 nt
	v_add_co_u32_e32 v80, vcc, s37, v80
	s_waitcnt lgkmcnt(0)
	v_lshl_add_u32 v84, v140, 2, 0
	v_addc_co_u32_e32 v81, vcc, 0, v81, vcc
	global_load_dwordx4 v[80:83], v[80:81], off offset:3072 nt
	v_add_u32_e32 v88, 0x22000, v84
	s_waitcnt vmcnt(2)
	v_lshlrev_b32_e32 v151, 16, v68
	v_lshlrev_b32_e32 v150, 16, v64
	ds_read_b128 v[108:111], v88 offset:2048
	ds_read_b128 v[122:125], v88
	ds_read_b128 v[84:87], v88 offset:16
	ds_read_b128 v[118:121], v88 offset:512
	ds_read_b128 v[114:117], v88 offset:1024
	ds_read_b128 v[104:107], v88 offset:1536
	ds_read_b128 v[100:103], v88 offset:2064
	ds_read_b128 v[96:99], v88 offset:528
	ds_read_b128 v[92:95], v88 offset:1040
	ds_read_b128 v[88:91], v88 offset:1552
	v_lshlrev_b32_e32 v153, 16, v72
	v_mov_b32_e32 v152, v151
	s_waitcnt lgkmcnt(0)
	v_pk_fma_f32 v[150:151], v[122:123], v[150:151], v[108:109] op_sel_hi:[0,1,0]
	v_mov_b32_e32 v154, v153
	v_pk_fma_f32 v[150:151], v[118:119], v[152:153], v[150:151] op_sel_hi:[0,1,1]
	v_and_or_b32 v112, v232, 64, v112
	v_lshlrev_b32_e32 v112, 2, v112
	ds_bpermute_b32 v138, v112, v139
	v_or_b32_e32 v112, 4, v112
	ds_bpermute_b32 v139, v112, v139
	v_lshl_add_u32 v112, v147, 2, 0
	s_mov_b32 s57, s35
	s_mov_b32 s73, 0
	s_mov_b64 s[58:59], -1
	s_waitcnt vmcnt(1)
	v_lshlrev_b32_e32 v155, 16, v76
	v_mov_b32_e32 v156, v155
	v_pk_fma_f32 v[150:151], v[114:115], v[154:155], v[150:151] op_sel_hi:[0,1,1]
	v_and_b32_e32 v155, 0xffff0000, v76
	s_waitcnt vmcnt(0)
	v_lshlrev_b32_e32 v157, 16, v80
	v_pk_fma_f32 v[150:151], v[104:105], v[156:157], v[150:151] op_sel_hi:[0,1,1]
	v_mul_f32_e32 v141, 0xbfb8aa3b, v150
	v_exp_f32_e32 v141, v141
	v_and_b32_e32 v157, 0xffff0000, v80
	v_mov_b32_e32 v156, v155
	v_add_f32_e32 v141, 1.0, v141
	v_rcp_f32_e32 v152, v141
	v_mul_f32_e32 v141, 0xbfb8aa3b, v151
	v_exp_f32_e32 v141, v141
	s_nop 0
	v_add_f32_e32 v141, 1.0, v141
	v_rcp_f32_e32 v153, v141
	v_mad_u64_u32 v[140:141], s[0:1], v140, s25, v[112:113]
	v_pk_mul_f32 v[150:151], v[150:151], v[152:153]
	s_waitcnt lgkmcnt(0)
	v_pk_mul_f32 v[150:151], v[150:151], v[138:139]
	v_and_b32_e32 v153, 0xffff0000, v72
	v_cvt_pk_bf16_f32 v158, v150, v151
	v_and_b32_e32 v151, 0xffff0000, v68
	v_and_b32_e32 v150, 0xffff0000, v64
	v_mov_b32_e32 v152, v151
	v_pk_fma_f32 v[108:109], v[122:123], v[150:151], v[108:109] op_sel:[1,0,1]
	v_mov_b32_e32 v154, v153
	v_pk_fma_f32 v[108:109], v[118:119], v[152:153], v[108:109] op_sel:[1,0,0]
	v_lshlrev_b32_e32 v119, 16, v81
	v_pk_fma_f32 v[108:109], v[114:115], v[154:155], v[108:109] op_sel:[1,0,0]
	v_lshlrev_b32_e32 v115, 16, v77
	v_pk_fma_f32 v[104:105], v[104:105], v[156:157], v[108:109] op_sel:[1,0,0]
	v_mov_b32_e32 v118, v115
	v_mul_f32_e32 v64, 0xbfb8aa3b, v104
	v_exp_f32_e32 v64, v64
	v_and_b32_e32 v77, 0xffff0000, v77
	v_and_b32_e32 v81, 0xffff0000, v81
	v_mov_b32_e32 v80, v77
	v_add_f32_e32 v64, 1.0, v64
	v_rcp_f32_e32 v108, v64
	v_mul_f32_e32 v64, 0xbfb8aa3b, v105
	v_exp_f32_e32 v64, v64
	s_nop 0
	v_add_f32_e32 v64, 1.0, v64
	v_rcp_f32_e32 v109, v64
	v_add_u32_e32 v64, 0x8800, v140
	v_pk_mul_f32 v[104:105], v[104:105], v[108:109]
	s_nop 0
	v_pk_mul_f32 v[104:105], v[104:105], v[138:139]
	v_lshlrev_b32_e32 v109, 16, v73
	v_cvt_pk_bf16_f32 v68, v104, v105
	v_lshlrev_b32_e32 v104, 16, v65
	v_lshlrev_b32_e32 v105, 16, v69
	v_mov_b32_e32 v108, v105
	v_pk_fma_f32 v[104:105], v[124:125], v[104:105], v[110:111] op_sel_hi:[0,1,0]
	v_mov_b32_e32 v114, v109
	v_pk_fma_f32 v[104:105], v[120:121], v[108:109], v[104:105] op_sel_hi:[0,1,1]
	v_pk_fma_f32 v[104:105], v[116:117], v[114:115], v[104:105] op_sel_hi:[0,1,1]
	v_pk_fma_f32 v[104:105], v[106:107], v[118:119], v[104:105] op_sel_hi:[0,1,1]
	ds_write2_b32 v64, v158, v68 offset1:36
	v_mul_f32_e32 v68, 0xbfb8aa3b, v104
	v_exp_f32_e32 v68, v68
	v_and_b32_e32 v69, 0xffff0000, v69
	v_mov_b32_e32 v106, v111
; #define LAS __attribute__((address_space(3)))
; DI unsigned pk2(float lo, float hi) { f32x2n v = {lo, hi}; bf16x2n b = __builtin_convertvector(v, bf16x2n); return __builtin_bit_cast(unsigned, b); }
; DI float silu(float y) { return y * frcp(1.0f + __expf(-y)); }
; DI void conv2(const u32x4 (&x)[5], const LAS float* cw, int dd, float (&y0)[8], float (&y1)[8]) {
;     float xf[5][8];
; #pragma unroll
;     for (int r = 0; r < 5; ++r) { xf[r][0] = bflo(x[r].x); xf[r][1] = bfhi(x[r].x); xf[r][2] = bflo(x[r].y); xf[r][3] = bfhi(x[r].y); xf[r][4] = bflo(x[r].z); xf[r][5] = bfhi(x[r].z); xf[r][6] = bflo(x[r].w); xf[r][7] = bfhi(x[r].w); }
; #pragma unroll
;     for (int j = 0; j < 8; ++j) { const float b = cw[4 * 128 + dd + j]; float a0 = b, a1 = b;
; #pragma unroll
;         for (int tp = 0; tp < 4; ++tp) { const float c = cw[tp * 128 + dd + j]; a0 += xf[tp][j] * c; a1 += xf[tp + 1][j] * c; }
;         y0[j] = silu(a0); y1[j] = silu(a1); }
; template <bool P2>
; DI void ml_pass(LAS unsigned char* lds, const bf16_t* PROJ, const float* GATES, float* STATE, float* SC, bf16_t* YM,
;                 const float* convw, const float* convb, const float* ogain, int G, int bid) {
;     ...
;                 float y0[8], y1[8]; conv2(xr, cw + 640, 8 * pc, y0, y1);
;                 if (P2) { u32x4 o; o.x = pk2(y0[0], y0[1]); o.y = pk2(y0[2], y0[3]); o.z = pk2(y0[4], y0[5]); o.w = pk2(y0[6], y0[7]); *(LAS u32x4*)(Ks + (2 * sp) * 136 + 8 * pc) = o;
;                     o.x = pk2(y1[0], y1[1]); o.y = pk2(y1[2], y1[3]); o.z = pk2(y1[4], y1[5]); o.w = pk2(y1[6], y1[7]); *(LAS u32x4*)(Ks + (2 * sp + 1) * 136 + 8 * pc) = o; }
;                 const float wk0 = __shfl(wk, 2 * sp), wk1 = __shfl(wk, 2 * sp + 1);
; #pragma unroll
;                 for (int j = 0; j < 8; ++j) Kt32[(8 * pc + j) * 36 + sp] = pk2(y0[j] * wk0, y1[j] * wk1);
	v_and_b32_e32 v73, 0xffff0000, v73
	v_add_f32_e32 v68, 1.0, v68
	v_rcp_f32_e32 v108, v68
	v_mul_f32_e32 v68, 0xbfb8aa3b, v105
	v_exp_f32_e32 v68, v68
	v_mov_b32_e32 v72, v69
	v_mov_b32_e32 v76, v73
	v_add_f32_e32 v68, 1.0, v68
	v_rcp_f32_e32 v109, v68
	v_and_b32_e32 v68, 0xffff0000, v65
	v_pk_mul_f32 v[104:105], v[104:105], v[108:109]
	s_nop 0
	v_pk_mul_f32 v[104:105], v[104:105], v[138:139]
	s_nop 0
	v_cvt_pk_bf16_f32 v105, v104, v105
	v_mov_b32_e32 v104, v125
	v_pk_fma_f32 v[68:69], v[104:105], v[68:69], v[106:107] op_sel_hi:[0,1,0]
	v_mov_b32_e32 v104, v121
	v_pk_fma_f32 v[68:69], v[104:105], v[72:73], v[68:69] op_sel_hi:[0,1,1]
	v_mov_b32_e32 v72, v117
	v_pk_fma_f32 v[68:69], v[72:73], v[76:77], v[68:69] op_sel_hi:[0,1,1]
	v_mov_b32_e32 v72, v107
	v_pk_fma_f32 v[68:69], v[72:73], v[80:81], v[68:69] op_sel_hi:[0,1,1]
	v_mul_f32_e32 v65, 0xbfb8aa3b, v68
	v_exp_f32_e32 v65, v65
	v_lshlrev_b32_e32 v77, 16, v78
	v_lshlrev_b32_e32 v81, 16, v82
	v_mov_b32_e32 v80, v77
	v_add_f32_e32 v65, 1.0, v65
	v_rcp_f32_e32 v72, v65
	v_mul_f32_e32 v65, 0xbfb8aa3b, v69
	v_exp_f32_e32 v65, v65
	s_nop 0
	v_add_f32_e32 v65, 1.0, v65
	v_rcp_f32_e32 v73, v65
	s_nop 0
	v_pk_mul_f32 v[68:69], v[68:69], v[72:73]
	s_nop 0
	v_pk_mul_f32 v[68:69], v[68:69], v[138:139]
	v_lshlrev_b32_e32 v73, 16, v74
	v_cvt_pk_bf16_f32 v65, v68, v69
	v_lshlrev_b32_e32 v69, 16, v70
	v_lshlrev_b32_e32 v68, 16, v66
	v_mov_b32_e32 v72, v69
	v_pk_fma_f32 v[68:69], v[84:85], v[68:69], v[100:101] op_sel_hi:[0,1,0]
	v_mov_b32_e32 v76, v73
	v_pk_fma_f32 v[68:69], v[96:97], v[72:73], v[68:69] op_sel_hi:[0,1,1]
	v_pk_fma_f32 v[68:69], v[92:93], v[76:77], v[68:69] op_sel_hi:[0,1,1]
	v_pk_fma_f32 v[68:69], v[88:89], v[80:81], v[68:69] op_sel_hi:[0,1,1]
	ds_write2_b32 v64, v105, v65 offset0:72 offset1:108
	v_mul_f32_e32 v65, 0xbfb8aa3b, v68
	v_exp_f32_e32 v65, v65
	v_and_b32_e32 v77, 0xffff0000, v78
	v_and_b32_e32 v81, 0xffff0000, v82
	v_mov_b32_e32 v80, v77
	v_add_f32_e32 v65, 1.0, v65
	v_rcp_f32_e32 v72, v65
	v_mul_f32_e32 v65, 0xbfb8aa3b, v69
	v_exp_f32_e32 v65, v65
	s_nop 0
	v_add_f32_e32 v65, 1.0, v65
	v_rcp_f32_e32 v73, v65
	s_nop 0
	v_pk_mul_f32 v[68:69], v[68:69], v[72:73]
	s_nop 0
	v_pk_mul_f32 v[68:69], v[68:69], v[138:139]
	v_and_b32_e32 v73, 0xffff0000, v74
	v_cvt_pk_bf16_f32 v65, v68, v69
	v_and_b32_e32 v69, 0xffff0000, v70
	v_and_b32_e32 v68, 0xffff0000, v66
	v_mov_b32_e32 v72, v69
	v_pk_fma_f32 v[68:69], v[84:85], v[68:69], v[100:101] op_sel:[1,0,1]
	v_mov_b32_e32 v76, v73
	v_pk_fma_f32 v[68:69], v[96:97], v[72:73], v[68:69] op_sel:[1,0,0]
	v_mov_b32_e32 v74, v103
	v_pk_fma_f32 v[68:69], v[92:93], v[76:77], v[68:69] op_sel:[1,0,0]
	v_lshlrev_b32_e32 v77, 16, v83
	v_pk_fma_f32 v[68:69], v[88:89], v[80:81], v[68:69] op_sel:[1,0,0]
	s_nop 0
	v_mul_f32_e32 v66, 0xbfb8aa3b, v68
	v_exp_f32_e32 v66, v66
	s_nop 0
	v_add_f32_e32 v66, 1.0, v66
	v_rcp_f32_e32 v72, v66
	v_mul_f32_e32 v66, 0xbfb8aa3b, v69
	v_exp_f32_e32 v66, v66
	s_nop 0
	v_add_f32_e32 v66, 1.0, v66
	v_rcp_f32_e32 v73, v66
	s_nop 0
	v_pk_mul_f32 v[68:69], v[68:69], v[72:73]
	s_nop 0
	v_pk_mul_f32 v[68:69], v[68:69], v[138:139]
	v_lshlrev_b32_e32 v73, 16, v79
	v_cvt_pk_bf16_f32 v66, v68, v69
	ds_write2_b32 v64, v65, v66 offset0:144 offset1:180
	v_lshlrev_b32_e32 v64, 16, v67
	v_lshlrev_b32_e32 v65, 16, v71
	v_lshlrev_b32_e32 v69, 16, v75
	v_mov_b32_e32 v68, v65
	v_pk_fma_f32 v[64:65], v[86:87], v[64:65], v[102:103] op_sel_hi:[0,1,0]
	v_mov_b32_e32 v72, v69
	v_pk_fma_f32 v[64:65], v[98:99], v[68:69], v[64:65] op_sel_hi:[0,1,1]
	v_mov_b32_e32 v76, v73
	v_pk_fma_f32 v[64:65], v[94:95], v[72:73], v[64:65] op_sel_hi:[0,1,1]
	v_pk_fma_f32 v[64:65], v[90:91], v[76:77], v[64:65] op_sel_hi:[0,1,1]
	v_mul_f32_e32 v66, 0xbfb8aa3b, v64
	v_exp_f32_e32 v66, v66
	v_mov_b32_e32 v72, v87
	v_add_f32_e32 v66, 1.0, v66
	v_rcp_f32_e32 v68, v66
	v_mul_f32_e32 v66, 0xbfb8aa3b, v65
	v_exp_f32_e32 v66, v66
	s_nop 0
	v_add_f32_e32 v66, 1.0, v66
	v_rcp_f32_e32 v69, v66
	s_nop 0
	v_pk_mul_f32 v[64:65], v[64:65], v[68:69]
	s_nop 0
	v_pk_mul_f32 v[64:65], v[64:65], v[138:139]
	v_and_b32_e32 v69, 0xffff0000, v79
	v_cvt_pk_bf16_f32 v64, v64, v65
	ds_write_b32 v140, v64 offset:35680
	v_and_b32_e32 v65, 0xffff0000, v71
	v_and_b32_e32 v64, 0xffff0000, v67
	v_and_b32_e32 v67, 0xffff0000, v75
	v_mov_b32_e32 v66, v65
	v_pk_fma_f32 v[64:65], v[72:73], v[64:65], v[74:75] op_sel_hi:[0,1,0]
	v_mov_b32_e32 v72, v99
	v_mov_b32_e32 v68, v67
	v_pk_fma_f32 v[64:65], v[72:73], v[66:67], v[64:65] op_sel_hi:[0,1,1]
	v_mov_b32_e32 v66, v95
	v_and_b32_e32 v71, 0xffff0000, v83
	v_mov_b32_e32 v70, v69
	v_pk_fma_f32 v[64:65], v[66:67], v[68:69], v[64:65] op_sel_hi:[0,1,1]
	v_mov_b32_e32 v66, v91
	v_pk_fma_f32 v[64:65], v[66:67], v[70:71], v[64:65] op_sel_hi:[0,1,1]
	v_mul_f32_e32 v66, 0xbfb8aa3b, v64
	v_mul_f32_e32 v67, 0xbfb8aa3b, v65
	v_exp_f32_e32 v66, v66
	v_exp_f32_e32 v67, v67
	v_add_f32_e32 v66, 1.0, v66
	v_add_f32_e32 v67, 1.0, v67
	v_rcp_f32_e32 v66, v66
	v_rcp_f32_e32 v67, v67
	s_nop 0
	v_pk_mul_f32 v[64:65], v[64:65], v[66:67]
	s_nop 0
	v_pk_mul_f32 v[64:65], v[64:65], v[138:139]
	s_nop 0
	v_cvt_pk_bf16_f32 v66, v64, v65
	v_or_b32_e32 v64, 7, v149
	v_mad_u64_u32 v[64:65], s[0:1], v64, s25, v[112:113]
	ds_write_b32 v64, v66 offset:34816
	v_lshl_add_u64 v[64:65], v[136:137], 0, s[56:57]
; #define LAS __attribute__((address_space(3)))
; DI void lbar() { asm volatile("s_waitcnt lgkmcnt(0)" ::: "memory"); __builtin_amdgcn_s_barrier(); asm volatile("" ::: "memory"); }
; DI f32x16 mfma32(bf16x8 a, bf16x8 b, f32x16 c) { return __builtin_amdgcn_mfma_f32_32x32x16_bf16(a, b, c, 0, 0, 0); }
; template <bool P2>
; DI void ml_pass(LAS unsigned char* lds, const bf16_t* PROJ, const float* GATES, float* STATE, float* SC, bf16_t* YM,
;                 const float* convw, const float* convb, const float* ogain, int G, int bid) {
;     ...
;             for (int it = 0; it < 2; ++it) { const int idx = tid + 512 * it, sp2 = idx & 31, pc2 = idx >> 5;
;                 const bf16_t* vb = PROJ + (row0 + 2 * sp2) * 3072 + 1024 + 256 * h + 8 * pc2;
;                 const u32x4 r0 = *(const u32x4*)vb, r1 = *(const u32x4*)(vb + 3072);
;                 LAS unsigned* dst = Vt32 + (8 * pc2) * 36 + sp2;
;                 dst[0 * 36] = (r0.x & 0xffffu) | (r1.x << 16); dst[1 * 36] = (r0.x >> 16) | (r1.x & 0xffff0000u);
;                 dst[2 * 36] = (r0.y & 0xffffu) | (r1.y << 16); dst[3 * 36] = (r0.y >> 16) | (r1.y & 0xffff0000u);
;                 dst[4 * 36] = (r0.z & 0xffffu) | (r1.z << 16); dst[5 * 36] = (r0.z >> 16) | (r1.z & 0xffff0000u);
;                 dst[6 * 36] = (r0.w & 0xffffu) | (r1.w << 16); dst[7 * 36] = (r0.w >> 16) | (r1.w & 0xffff0000u); }
;             lbar();
;     ...
;             bf16x8 vf[4];
; #pragma unroll
;             for (int kq = 0; kq < 4; ++kq) vf[kq] = *(const LAS bf16x8*)(Vt + (32 * w + l31) * 72 + 16 * kq + 8 * hi);
;             if (P2) {
; #pragma unroll
;                 for (int kq = 0; kq < 4; ++kq)
; #pragma unroll
;                     for (int tt = 0; tt < 2; ++tt) { const bf16x8 wf = *(const LAS bf16x8*)(Ws + (32 * tt + l31) * 72 + 16 * kq + 8 * hi); oacc[tt] = mfma32(vf[kq], wf, oacc[tt]); }
;             }
;             asm volatile("" ::: "memory");
;             if (!P2 || c < 7) {
; #pragma unroll
;             for (int dt = 0; dt < 4; ++dt) {
; #pragma unroll
;                 for (int i = 0; i < 16; ++i) Ct[dt][i] *= decay;
; #pragma unroll
;                 for (int kq = 0; kq < 4; ++kq) { const bf16x8 kf = *(const LAS bf16x8*)(Kt + (32 * dt + l31) * 72 + 16 * kq + 8 * hi); Ct[dt] = mfma32(kf, vf[kq], Ct[dt]); }
;             }
.LBB0_205:
	v_cndmask_b32_e64 v66, 0, 1, s[58:59]
	v_cmp_ne_u32_e64 s[0:1], 1, v66
	v_add_u32_e32 v66, s73, v146
	v_ashrrev_i32_e32 v66, 2, v66
	v_and_b32_e32 v74, -8, v66
	v_ashrrev_i32_e32 v75, 31, v74
	v_lshl_add_u64 v[70:71], v[74:75], 1, v[64:65]
	global_load_dwordx4 v[66:69], v[70:71], off offset:2048 nt
	v_add_co_u32_e32 v70, vcc, 0x2000, v70
	v_mad_u64_u32 v[74:75], s[58:59], v74, s25, v[112:113]
	s_nop 0
	v_addc_co_u32_e32 v71, vcc, 0, v71, vcc
	global_load_dwordx4 v[70:73], v[70:71], off nt
	s_movk_i32 s73, 0x200
	s_mov_b64 s[58:59], 0
	s_and_b64 vcc, exec, s[0:1]
	s_waitcnt vmcnt(1)
	v_and_b32_e32 v75, 0xffff, v66
	v_lshrrev_b32_e32 v66, 16, v66
	s_waitcnt vmcnt(0)
	v_lshl_or_b32 v75, v70, 16, v75
	v_and_or_b32 v66, v70, s27, v66
	v_add_u32_e32 v70, 0xd000, v74
	ds_write2_b32 v70, v75, v66 offset1:36
	v_and_b32_e32 v66, 0xffff, v67
	v_lshrrev_b32_e32 v67, 16, v67
	v_lshl_or_b32 v66, v71, 16, v66
	v_and_or_b32 v67, v71, s27, v67
	ds_write2_b32 v70, v66, v67 offset0:72 offset1:108
	v_and_b32_e32 v66, 0xffff, v68
	v_lshrrev_b32_e32 v67, 16, v68
	v_lshl_or_b32 v66, v72, 16, v66
	v_and_or_b32 v67, v72, s27, v67
	ds_write2_b32 v70, v66, v67 offset0:144 offset1:180
	v_and_b32_e32 v66, 0xffff, v69
	v_lshrrev_b32_e32 v67, 16, v69
	v_lshl_or_b32 v66, v73, 16, v66
	v_and_or_b32 v67, v73, s27, v67
	ds_write2_b32 v70, v66, v67 offset0:216 offset1:252
	s_cbranch_vccz .LBB0_205
	v_sub_f32_e32 v64, v148, v134
	v_mul_f32_e32 v64, 0x3fb8aa3b, v64
	v_exp_f32_e32 v80, v64
	s_lshr_b32 s0, s72, 1
	v_lshrrev_b32_e32 v65, 1, v146
	s_and_b32 s0, s0, 0xfffffe0
	v_and_b32_e32 v65, 16, v65
	s_waitcnt lgkmcnt(0)
	s_barrier
	v_or_b32_e32 v64, s0, v147
	v_add_u32_e32 v82, 0, v65
	v_mad_u64_u32 v[64:65], s[0:1], v64, s25, v[82:83]
	ds_read_b128 v[76:79], v64 offset:53248
	ds_read_b128 v[72:75], v64 offset:53280
	ds_read_b128 v[68:71], v64 offset:53312
	ds_read_b128 v[64:67], v64 offset:53344
	v_pk_mul_f32 v[62:63], v[62:63], v[80:81] op_sel_hi:[1,0]
	v_mad_u32_u24 v81, v147, s25, v82
	ds_read_b128 v[82:85], v81 offset:34816
	ds_read_b128 v[86:89], v81 offset:34848
	v_pk_mul_f32 v[60:61], v[60:61], v[80:81] op_sel_hi:[1,0]
	v_pk_mul_f32 v[58:59], v[58:59], v[80:81] op_sel_hi:[1,0]
	v_pk_mul_f32 v[56:57], v[56:57], v[80:81] op_sel_hi:[1,0]
	v_pk_mul_f32 v[54:55], v[54:55], v[80:81] op_sel_hi:[1,0]
	v_pk_mul_f32 v[52:53], v[52:53], v[80:81] op_sel_hi:[1,0]
	v_pk_mul_f32 v[50:51], v[50:51], v[80:81] op_sel_hi:[1,0]
	v_pk_mul_f32 v[48:49], v[48:49], v[80:81] op_sel_hi:[1,0]
	v_pk_mul_f32 v[30:31], v[30:31], v[80:81] op_sel_hi:[1,0]
	v_pk_mul_f32 v[28:29], v[28:29], v[80:81] op_sel_hi:[1,0]
	s_waitcnt lgkmcnt(1)
	v_mfma_f32_32x32x16_bf16 v[48:63], v[82:85], v[76:79], v[48:63]
	v_mul_f32_e64 v26, v26, v80
	v_mul_f32_e64 v27, v27, v80
	v_mul_f32_e64 v24, v24, v80
	v_mul_f32_e64 v25, v25, v80
	v_mul_f32_e64 v22, v22, v80
	v_mul_f32_e64 v23, v23, v80
	v_pk_mul_f32 v[20:21], v[20:21], v[80:81] op_sel_hi:[1,0]
	v_pk_mul_f32 v[18:19], v[18:19], v[80:81] op_sel_hi:[1,0]
	v_pk_mul_f32 v[16:17], v[16:17], v[80:81] op_sel_hi:[1,0]
	v_pk_mul_f32 v[46:47], v[46:47], v[80:81] op_sel_hi:[1,0]
	s_waitcnt lgkmcnt(0)
	v_mfma_f32_32x32x16_bf16 v[48:63], v[86:89], v[72:75], v[48:63]
	ds_read_b128 v[82:85], v81 offset:34880
	ds_read_b128 v[86:89], v81 offset:34912
	v_mul_f32_e64 v44, v44, v80
	v_mul_f32_e64 v45, v45, v80
	v_mul_f32_e64 v42, v42, v80
	v_mul_f32_e64 v43, v43, v80
	v_pk_mul_f32 v[40:41], v[40:41], v[80:81] op_sel_hi:[1,0]
	v_pk_mul_f32 v[38:39], v[38:39], v[80:81] op_sel_hi:[1,0]
	v_pk_mul_f32 v[36:37], v[36:37], v[80:81] op_sel_hi:[1,0]
	v_pk_mul_f32 v[34:35], v[34:35], v[80:81] op_sel_hi:[1,0]
	s_waitcnt lgkmcnt(1)
	v_mfma_f32_32x32x16_bf16 v[48:63], v[82:85], v[68:71], v[48:63]
	ds_read_b128 v[82:85], v81 offset:39424
	v_mul_f32_e64 v32, v32, v80
	v_mul_f32_e64 v33, v33, v80
	v_mul_f32_e64 v14, v14, v80
	v_mul_f32_e64 v15, v15, v80
	v_pk_mul_f32 v[12:13], v[12:13], v[80:81] op_sel_hi:[1,0]
	v_pk_mul_f32 v[10:11], v[10:11], v[80:81] op_sel_hi:[1,0]
	v_pk_mul_f32 v[8:9], v[8:9], v[80:81] op_sel_hi:[1,0]
	v_pk_mul_f32 v[6:7], v[6:7], v[80:81] op_sel_hi:[1,0]
	s_waitcnt lgkmcnt(1)
	v_mfma_f32_32x32x16_bf16 v[48:63], v[86:89], v[64:67], v[48:63]
	ds_read_b128 v[86:89], v81 offset:39456
	v_mul_f32_e64 v4, v4, v80
	v_mul_f32_e64 v5, v5, v80
	v_mul_f32_e64 v2, v2, v80
	v_mul_f32_e64 v3, v3, v80
	v_pk_mul_f32 v[0:1], v[0:1], v[80:81] op_sel_hi:[1,0]
	v_cmp_gt_i32_e32 vcc, s30, v146
	s_waitcnt lgkmcnt(1)
	v_mfma_f32_32x32x16_bf16 v[16:31], v[82:85], v[76:79], v[16:31]
	s_waitcnt lgkmcnt(0)
	v_mfma_f32_32x32x16_bf16 v[16:31], v[86:89], v[72:75], v[16:31]
	ds_read_b128 v[82:85], v81 offset:39488
	ds_read_b128 v[86:89], v81 offset:39520
	s_waitcnt lgkmcnt(1)
	v_mfma_f32_32x32x16_bf16 v[16:31], v[82:85], v[68:71], v[16:31]
	ds_read_b128 v[82:85], v81 offset:44032
	s_waitcnt lgkmcnt(1)
	v_mfma_f32_32x32x16_bf16 v[16:31], v[86:89], v[64:67], v[16:31]
	ds_read_b128 v[86:89], v81 offset:44064
	s_waitcnt lgkmcnt(1)
	v_mfma_f32_32x32x16_bf16 v[32:47], v[82:85], v[76:79], v[32:47]
	s_waitcnt lgkmcnt(0)
	v_mfma_f32_32x32x16_bf16 v[32:47], v[86:89], v[72:75], v[32:47]
	ds_read_b128 v[82:85], v81 offset:44096
	ds_read_b128 v[86:89], v81 offset:44128
	s_waitcnt lgkmcnt(1)
	v_mfma_f32_32x32x16_bf16 v[32:47], v[82:85], v[68:71], v[32:47]
	ds_read_b128 v[82:85], v81 offset:48640
	s_waitcnt lgkmcnt(1)
	v_mfma_f32_32x32x16_bf16 v[32:47], v[86:89], v[64:67], v[32:47]
	ds_read_b128 v[86:89], v81 offset:48672
	s_waitcnt lgkmcnt(1)
	v_mfma_f32_32x32x16_bf16 v[0:15], v[82:85], v[76:79], v[0:15]
	s_waitcnt lgkmcnt(0)
	v_mfma_f32_32x32x16_bf16 v[0:15], v[86:89], v[72:75], v[0:15]
	ds_read_b128 v[72:75], v81 offset:48704
	ds_read_b128 v[76:79], v81 offset:48736
	s_waitcnt lgkmcnt(1)
	v_mfma_f32_32x32x16_bf16 v[0:15], v[72:75], v[68:71], v[0:15]
	s_waitcnt lgkmcnt(0)
	v_mfma_f32_32x32x16_bf16 v[0:15], v[76:79], v[64:67], v[0:15]
	s_and_saveexec_b64 s[0:1], vcc
	s_cbranch_execz .LBB0_195
; #define LAS __attribute__((address_space(3)))
; template <bool P2>
; DI void ml_pass(LAS unsigned char* lds, const bf16_t* PROJ, const float* GATES, float* STATE, float* SC, bf16_t* YM,
;                 const float* convw, const float* convb, const float* ogain, int G, int bid) {
;     ...
;             if (tid < 128) { float s = 0.f;
; #pragma unroll
;                 for (int q8 = 0; q8 < 8; ++q8) { const u32x4 kv = *(const LAS u32x4*)(Kt + tid * 72 + 8 * q8); s += (bflo(kv.x) + bfhi(kv.x)) + (bflo(kv.y) + bfhi(kv.y)) + (bflo(kv.z) + bfhi(kv.z)) + (bflo(kv.w) + bfhi(kv.w)); }
;                 ns[tid] = decay * ns[tid] + s; }
	v_mul_lo_u32 v64, v146, s25
	v_add_u32_e32 v81, 0, v64
	ds_read_b128 v[64:67], v81 offset:34816
	ds_read_b128 v[68:71], v81 offset:34832
	ds_read_b128 v[72:75], v81 offset:34848
	ds_read_b128 v[76:79], v81 offset:34864
	s_waitcnt lgkmcnt(3)
	v_lshlrev_b32_e32 v82, 16, v64
	s_waitcnt lgkmcnt(2)
	v_lshlrev_b32_e32 v83, 16, v68
	v_and_b32_e32 v85, 0xffff0000, v68
	v_and_b32_e32 v84, 0xffff0000, v64
	v_pk_add_f32 v[82:83], v[82:83], v[84:85]
	v_lshlrev_b32_e32 v85, 16, v69
	v_lshlrev_b32_e32 v84, 16, v65
	v_and_b32_e32 v69, 0xffff0000, v69
	v_and_b32_e32 v68, 0xffff0000, v65
	v_pk_add_f32 v[64:65], v[84:85], v[68:69]
	v_lshlrev_b32_e32 v69, 16, v70
	v_pk_add_f32 v[64:65], v[82:83], v[64:65]
	v_lshlrev_b32_e32 v68, 16, v66
	v_and_b32_e32 v83, 0xffff0000, v70
	v_and_b32_e32 v82, 0xffff0000, v66
	v_pk_add_f32 v[68:69], v[68:69], v[82:83]
	v_and_b32_e32 v70, 0xffff0000, v67
	v_pk_add_f32 v[64:65], v[68:69], v[64:65]
	v_lshlrev_b32_e32 v69, 16, v71
	v_lshlrev_b32_e32 v68, 16, v67
	v_and_b32_e32 v71, 0xffff0000, v71
	v_pk_add_f32 v[66:67], v[68:69], v[70:71]
	s_waitcnt lgkmcnt(1)
	v_and_b32_e32 v71, 0xffff0000, v75
	v_pk_add_f32 v[64:65], v[66:67], v[64:65]
	v_and_b32_e32 v67, 0xffff0000, v73
	v_add_f32_e32 v64, 0, v64
	v_add_f32_e32 v68, v64, v65
	v_lshlrev_b32_e32 v65, 16, v73
	v_lshlrev_b32_e32 v64, 16, v72
	v_and_b32_e32 v66, 0xffff0000, v72
	v_pk_add_f32 v[64:65], v[64:65], v[66:67]
	v_lshlrev_b32_e32 v67, 16, v75
	v_lshlrev_b32_e32 v66, 16, v74
	v_and_b32_e32 v70, 0xffff0000, v74
	v_pk_add_f32 v[64:65], v[64:65], v[64:65] op_sel:[0,1] op_sel_hi:[1,0]
	v_pk_add_f32 v[70:71], v[66:67], v[70:71]
	s_waitcnt lgkmcnt(0)
	v_lshlrev_b32_e32 v82, 16, v78
	v_pk_add_f32 v[72:73], v[70:71], v[64:65]
	v_lshlrev_b32_e32 v64, 16, v76
	v_and_b32_e32 v65, 0xffff0000, v76
	v_add_f32_e32 v74, v64, v65
	v_lshlrev_b32_e32 v64, 16, v77
	v_and_b32_e32 v65, 0xffff0000, v77
	v_add_f32_e32 v76, v64, v65
	ds_read_b128 v[64:67], v81 offset:34880
	s_waitcnt lgkmcnt(0)
	v_lshlrev_b32_e32 v75, 16, v65
	v_and_b32_e32 v77, 0xffff0000, v65
	v_lshlrev_b32_e32 v83, 16, v64
	v_and_b32_e32 v65, 0xffff0000, v64
	v_and_b32_e32 v64, 0xffff0000, v78
	v_pk_add_f32 v[64:65], v[82:83], v[64:65]
	v_pk_add_f32 v[74:75], v[74:75], v[76:77]
	v_lshlrev_b32_e32 v69, 16, v67
	v_pk_add_f32 v[64:65], v[64:65], v[74:75]
	v_pk_mov_b32 v[74:75], v[78:79], v[66:67] op_sel:[1,0]
	v_and_b32_e32 v84, 0xffff0000, v67
	v_lshlrev_b32_e32 v67, 16, v66
	v_lshlrev_b32_e32 v66, 16, v79
	v_and_b32_e32 v75, 0xffff0000, v75
	v_and_b32_e32 v74, 0xffff0000, v74
	v_pk_add_f32 v[66:67], v[66:67], v[74:75]
	s_nop 0
	v_pk_add_f32 v[64:65], v[66:67], v[64:65]
	v_pk_add_f32 v[66:67], v[70:71], v[72:73] op_sel:[1,0] op_sel_hi:[0,1]
	v_mov_b32_e32 v67, v84
	v_pk_add_f32 v[66:67], v[68:69], v[66:67]
	s_nop 0
	v_pk_add_f32 v[64:65], v[66:67], v[64:65]
	ds_read_b128 v[66:69], v81 offset:34896
	v_pk_add_f32 v[64:65], v[64:65], v[64:65] op_sel:[0,1] op_sel_hi:[1,0]
	s_waitcnt lgkmcnt(0)
	v_lshlrev_b32_e32 v71, 16, v67
	v_lshlrev_b32_e32 v70, 16, v66
	v_and_b32_e32 v67, 0xffff0000, v67
	v_and_b32_e32 v66, 0xffff0000, v66
	v_pk_add_f32 v[66:67], v[70:71], v[66:67]
	v_lshlrev_b32_e32 v71, 16, v69
	v_lshlrev_b32_e32 v70, 16, v68
	v_and_b32_e32 v69, 0xffff0000, v69
	v_and_b32_e32 v68, 0xffff0000, v68
	v_pk_add_f32 v[66:67], v[66:67], v[66:67] op_sel:[0,1] op_sel_hi:[1,0]
	v_pk_add_f32 v[74:75], v[70:71], v[68:69]
	s_nop 0
	v_pk_add_f32 v[76:77], v[74:75], v[66:67]
	ds_read_b128 v[66:69], v81 offset:34912
	s_waitcnt lgkmcnt(0)
	v_lshlrev_b32_e32 v70, 16, v66
	v_and_b32_e32 v66, 0xffff0000, v66
	v_add_f32_e32 v66, v70, v66
	v_lshlrev_b32_e32 v70, 16, v67
	v_and_b32_e32 v67, 0xffff0000, v67
	v_add_f32_e32 v78, v70, v67
	ds_read_b128 v[70:73], v81 offset:34928
	v_lshlrev_b32_e32 v82, 16, v68
	s_waitcnt lgkmcnt(0)
	v_lshlrev_b32_e32 v67, 16, v71
	v_and_b32_e32 v79, 0xffff0000, v71
	v_lshlrev_b32_e32 v83, 16, v70
	v_and_b32_e32 v71, 0xffff0000, v70
	v_and_b32_e32 v70, 0xffff0000, v68
	v_pk_add_f32 v[70:71], v[82:83], v[70:71]
	v_pk_add_f32 v[66:67], v[66:67], v[78:79]
	v_lshlrev_b32_e32 v81, 16, v73
	v_pk_add_f32 v[66:67], v[70:71], v[66:67]
	v_pk_mov_b32 v[70:71], v[68:69], v[72:73] op_sel:[1,0]
	v_and_b32_e32 v84, 0xffff0000, v73
	v_lshlrev_b32_e32 v73, 16, v72
	v_lshlrev_b32_e32 v72, 16, v69
	v_and_b32_e32 v69, 0xffff0000, v71
	v_and_b32_e32 v68, 0xffff0000, v70
	v_pk_add_f32 v[68:69], v[72:73], v[68:69]
	v_mov_b32_e32 v65, v81
	v_pk_add_f32 v[66:67], v[68:69], v[66:67]
	v_pk_add_f32 v[68:69], v[74:75], v[76:77] op_sel:[1,0] op_sel_hi:[0,1]
	v_mov_b32_e32 v69, v84
	v_pk_add_f32 v[64:65], v[64:65], v[68:69]
	s_nop 0
	v_pk_add_f32 v[64:65], v[64:65], v[66:67]
	s_nop 0
	v_add_f32_e32 v64, v64, v65
	v_lshl_add_u32 v65, v146, 2, 0
	v_add_u32_e32 v65, 0x20800, v65
	ds_read_b32 v66, v65
	s_waitcnt lgkmcnt(0)
	v_fmac_f32_e32 v64, v80, v66
	ds_write_b32 v65, v64
	s_branch .LBB0_195
